# scan compute variant F only (cc read as one b128 per two steps, computed LDS wait counts), on top of v112
# speedup vs baseline: 1.0060x; 1.0011x over previous
.Lsc_chunk:
	s_and_b32 s1, s0, 1
	s_lshl_b32 s2, s1, 12
	s_mulk_i32 s1, 0x6080
	s_add_i32 s1, s1, s3
	v_add_u32_e32 v10, s1, v46
	v_add_u32_e32 v11, s1, v47
	v_add_u32_e32 v13, s2, v48
	s_add_i32 s1, s1, 0x6000
	v_mov_b32_e32 v12, s1
	ds_read_b128 v[52:55], v10 offset:0
	ds_read_b64 v[72:73], v11 offset:0
	ds_read_b128 v[64:67], v10 offset:12288
	ds_read_b128 v[60:63], v10 offset:8192
	ds_read_b128 v[56:59], v10 offset:4096
	ds_read_b128 v[68:71], v10 offset:16384
	ds_read_b128 v[124:127], v12 offset:0
	ds_read_b128 v[76:79], v10 offset:256
	ds_read_b64 v[96:97], v11 offset:256
	ds_read_b128 v[88:91], v10 offset:12544
	ds_read_b128 v[84:87], v10 offset:8448
	ds_read_b128 v[80:83], v10 offset:4352
	ds_read_b128 v[92:95], v10 offset:16640
	s_waitcnt lgkmcnt(6)
	ds_read_b128 v[100:103], v10 offset:512
	ds_read_b64 v[120:121], v11 offset:512
	ds_read_b128 v[112:115], v10 offset:12800
	ds_read_b128 v[108:111], v10 offset:8704
	ds_read_b128 v[104:107], v10 offset:4608
	ds_read_b128 v[116:119], v10 offset:16896
	ds_read_b128 v[128:131], v12 offset:16
	v_pk_mul_f32 v[16:17], v[0:1], v[52:53]
	v_pk_mul_f32 v[18:19], v[4:5], v[52:53]
	v_pk_fma_f32 v[16:17], v[2:3], v[54:55], v[16:17]
	v_pk_fma_f32 v[18:19], v[6:7], v[54:55], v[18:19]
	v_pk_mul_f32 v[14:15], v[72:73], s[4:5] op_sel_hi:[1,0]
	v_pk_mul_f32 v[20:21], v[64:65], v[14:15] op_sel_hi:[1,0]
	v_pk_mul_f32 v[22:23], v[66:67], v[14:15] op_sel_hi:[1,0]
	v_add_f32_e32 v32, v16, v17
	v_add_f32_e32 v33, v18, v19
	v_pk_mul_f32 v[24:25], v[64:65], v[14:15] op_sel:[0,1] op_sel_hi:[1,1]
	v_pk_mul_f32 v[26:27], v[66:67], v[14:15] op_sel:[0,1] op_sel_hi:[1,1]
	v_cndmask_b32_e64 v34, v32, v33, s[6:7]
	v_cndmask_b32_e64 v35, v33, v32, s[6:7]
	v_pk_mul_f32 v[38:39], v[14:15], v[124:125] op_sel:[0,1] op_sel_hi:[1,1]
	v_pk_fma_f32 v[20:21], v[60:61], v[8:9], v[20:21] op_sel_hi:[1,0,1]
	v_add_f32_dpp v35, v34, v35 row_ror:8 row_mask:0xf bank_mask:0xf bound_ctrl:1
	v_pk_fma_f32 v[22:23], v[62:63], v[8:9], v[22:23] op_sel_hi:[1,0,1]
	v_pk_fma_f32 v[24:25], v[60:61], v[8:9], v[24:25] op_sel:[0,1,0] op_sel_hi:[1,1,1]
	v_pk_fma_f32 v[26:27], v[62:63], v[8:9], v[26:27] op_sel:[0,1,0] op_sel_hi:[1,1,1]
	v_add_f32_dpp v35, v35, v35 quad_perm:[1,0,3,2] row_mask:0xf bank_mask:0xf bound_ctrl:1
	v_pk_fma_f32 v[0:1], v[0:1], v[56:57], v[20:21]
	v_pk_fma_f32 v[2:3], v[2:3], v[58:59], v[22:23]
	v_pk_fma_f32 v[4:5], v[4:5], v[56:57], v[24:25]
	v_add_f32_dpp v35, v35, v35 quad_perm:[2,3,0,1] row_mask:0xf bank_mask:0xf bound_ctrl:1
	v_pk_fma_f32 v[6:7], v[6:7], v[58:59], v[26:27]
	v_pk_mul_f32 v[28:29], v[0:1], v[68:69]
	v_pk_fma_f32 v[38:39], v[8:9], v[124:125], v[38:39] op_sel_hi:[1,0,1]
	v_add_f32_dpp v35, v35, v35 row_half_mirror row_mask:0xf bank_mask:0xf bound_ctrl:1
	v_pk_mul_f32 v[30:31], v[4:5], v[68:69]
	v_pk_fma_f32 v[28:29], v[2:3], v[70:71], v[28:29]
	v_pk_fma_f32 v[30:31], v[6:7], v[70:71], v[30:31]
	v_mov_b32_dpp v34, v35 row_ror:8 row_mask:0xf bank_mask:0xf
	v_add_f32_e32 v16, v28, v29
	v_add_f32_e32 v17, v30, v31
	v_cndmask_b32_e64 v32, v34, v35, s[6:7]
	v_cndmask_b32_e64 v33, v35, v34, s[6:7]
	v_cndmask_b32_e64 v18, v16, v17, s[6:7]
	v_cndmask_b32_e64 v19, v17, v16, s[6:7]
	v_pk_add_f32 v[8:9], v[32:33], v[38:39] neg_lo:[1,1] neg_hi:[1,1]
	s_nop 0
	v_add_f32_dpp v36, v18, v19 row_ror:8 row_mask:0xf bank_mask:0xf bound_ctrl:1
	ds_write_b32 v13, v36 offset:0
	s_waitcnt lgkmcnt(8)
	ds_read_b128 v[52:55], v10 offset:768
	ds_read_b64 v[72:73], v11 offset:768
	ds_read_b128 v[64:67], v10 offset:13056
	ds_read_b128 v[60:63], v10 offset:8960
	ds_read_b128 v[56:59], v10 offset:4864
	ds_read_b128 v[68:71], v10 offset:17152
	v_pk_mul_f32 v[16:17], v[0:1], v[76:77]
	v_pk_mul_f32 v[18:19], v[4:5], v[76:77]
	v_pk_fma_f32 v[16:17], v[2:3], v[78:79], v[16:17]
	v_pk_fma_f32 v[18:19], v[6:7], v[78:79], v[18:19]
	v_pk_mul_f32 v[14:15], v[96:97], s[4:5] op_sel_hi:[1,0]
	v_pk_mul_f32 v[20:21], v[88:89], v[14:15] op_sel_hi:[1,0]
	v_pk_mul_f32 v[22:23], v[90:91], v[14:15] op_sel_hi:[1,0]
	v_add_f32_e32 v32, v16, v17
	v_add_f32_e32 v33, v18, v19
	v_pk_mul_f32 v[24:25], v[88:89], v[14:15] op_sel:[0,1] op_sel_hi:[1,1]
	v_pk_mul_f32 v[26:27], v[90:91], v[14:15] op_sel:[0,1] op_sel_hi:[1,1]
	v_cndmask_b32_e64 v34, v32, v33, s[6:7]
	v_cndmask_b32_e64 v35, v33, v32, s[6:7]
	v_pk_mul_f32 v[38:39], v[14:15], v[126:127] op_sel:[0,1] op_sel_hi:[1,1]
	v_pk_fma_f32 v[20:21], v[84:85], v[8:9], v[20:21] op_sel_hi:[1,0,1]
	v_add_f32_dpp v35, v34, v35 row_ror:8 row_mask:0xf bank_mask:0xf bound_ctrl:1
	v_pk_fma_f32 v[22:23], v[86:87], v[8:9], v[22:23] op_sel_hi:[1,0,1]
	v_pk_fma_f32 v[24:25], v[84:85], v[8:9], v[24:25] op_sel:[0,1,0] op_sel_hi:[1,1,1]
	v_pk_fma_f32 v[26:27], v[86:87], v[8:9], v[26:27] op_sel:[0,1,0] op_sel_hi:[1,1,1]
	v_add_f32_dpp v35, v35, v35 quad_perm:[1,0,3,2] row_mask:0xf bank_mask:0xf bound_ctrl:1
	v_pk_fma_f32 v[0:1], v[0:1], v[80:81], v[20:21]
	v_pk_fma_f32 v[2:3], v[2:3], v[82:83], v[22:23]
	v_pk_fma_f32 v[4:5], v[4:5], v[80:81], v[24:25]
	v_add_f32_dpp v35, v35, v35 quad_perm:[2,3,0,1] row_mask:0xf bank_mask:0xf bound_ctrl:1
	v_pk_fma_f32 v[6:7], v[6:7], v[82:83], v[26:27]
	v_pk_mul_f32 v[28:29], v[0:1], v[92:93]
	v_pk_fma_f32 v[38:39], v[8:9], v[126:127], v[38:39] op_sel_hi:[1,0,1]
	v_add_f32_dpp v35, v35, v35 row_half_mirror row_mask:0xf bank_mask:0xf bound_ctrl:1
	v_pk_mul_f32 v[30:31], v[4:5], v[92:93]
	v_pk_fma_f32 v[28:29], v[2:3], v[94:95], v[28:29]
	v_pk_fma_f32 v[30:31], v[6:7], v[94:95], v[30:31]
	v_mov_b32_dpp v34, v35 row_ror:8 row_mask:0xf bank_mask:0xf
	v_add_f32_e32 v16, v28, v29
	v_add_f32_e32 v17, v30, v31
	v_cndmask_b32_e64 v32, v34, v35, s[6:7]
	v_cndmask_b32_e64 v33, v35, v34, s[6:7]
	v_cndmask_b32_e64 v18, v16, v17, s[6:7]
	v_cndmask_b32_e64 v19, v17, v16, s[6:7]
	v_pk_add_f32 v[8:9], v[32:33], v[38:39] neg_lo:[1,1] neg_hi:[1,1]
	s_nop 0
	v_add_f32_dpp v36, v18, v19 row_ror:8 row_mask:0xf bank_mask:0xf bound_ctrl:1
	ds_write_b32 v13, v36 offset:256
	s_waitcnt lgkmcnt(8)
	ds_read_b128 v[76:79], v10 offset:1024
	ds_read_b64 v[96:97], v11 offset:1024
	ds_read_b128 v[88:91], v10 offset:13312
	ds_read_b128 v[84:87], v10 offset:9216
	ds_read_b128 v[80:83], v10 offset:5120
	ds_read_b128 v[92:95], v10 offset:17408
	ds_read_b128 v[124:127], v12 offset:32
	v_pk_mul_f32 v[16:17], v[0:1], v[100:101]
	v_pk_mul_f32 v[18:19], v[4:5], v[100:101]
	v_pk_fma_f32 v[16:17], v[2:3], v[102:103], v[16:17]
	v_pk_fma_f32 v[18:19], v[6:7], v[102:103], v[18:19]
	v_pk_mul_f32 v[14:15], v[120:121], s[4:5] op_sel_hi:[1,0]
	v_pk_mul_f32 v[20:21], v[112:113], v[14:15] op_sel_hi:[1,0]
	v_pk_mul_f32 v[22:23], v[114:115], v[14:15] op_sel_hi:[1,0]
	v_add_f32_e32 v32, v16, v17
	v_add_f32_e32 v33, v18, v19
	v_pk_mul_f32 v[24:25], v[112:113], v[14:15] op_sel:[0,1] op_sel_hi:[1,1]
	v_pk_mul_f32 v[26:27], v[114:115], v[14:15] op_sel:[0,1] op_sel_hi:[1,1]
	v_cndmask_b32_e64 v34, v32, v33, s[6:7]
	v_cndmask_b32_e64 v35, v33, v32, s[6:7]
	v_pk_mul_f32 v[38:39], v[14:15], v[128:129] op_sel:[0,1] op_sel_hi:[1,1]
	v_pk_fma_f32 v[20:21], v[108:109], v[8:9], v[20:21] op_sel_hi:[1,0,1]
	v_add_f32_dpp v35, v34, v35 row_ror:8 row_mask:0xf bank_mask:0xf bound_ctrl:1
	v_pk_fma_f32 v[22:23], v[110:111], v[8:9], v[22:23] op_sel_hi:[1,0,1]
	v_pk_fma_f32 v[24:25], v[108:109], v[8:9], v[24:25] op_sel:[0,1,0] op_sel_hi:[1,1,1]
	v_pk_fma_f32 v[26:27], v[110:111], v[8:9], v[26:27] op_sel:[0,1,0] op_sel_hi:[1,1,1]
	v_add_f32_dpp v35, v35, v35 quad_perm:[1,0,3,2] row_mask:0xf bank_mask:0xf bound_ctrl:1
	v_pk_fma_f32 v[0:1], v[0:1], v[104:105], v[20:21]
	v_pk_fma_f32 v[2:3], v[2:3], v[106:107], v[22:23]
	v_pk_fma_f32 v[4:5], v[4:5], v[104:105], v[24:25]
	v_add_f32_dpp v35, v35, v35 quad_perm:[2,3,0,1] row_mask:0xf bank_mask:0xf bound_ctrl:1
	v_pk_fma_f32 v[6:7], v[6:7], v[106:107], v[26:27]
	v_pk_mul_f32 v[28:29], v[0:1], v[116:117]
	v_pk_fma_f32 v[38:39], v[8:9], v[128:129], v[38:39] op_sel_hi:[1,0,1]
	v_add_f32_dpp v35, v35, v35 row_half_mirror row_mask:0xf bank_mask:0xf bound_ctrl:1
	v_pk_mul_f32 v[30:31], v[4:5], v[116:117]
	v_pk_fma_f32 v[28:29], v[2:3], v[118:119], v[28:29]
	v_pk_fma_f32 v[30:31], v[6:7], v[118:119], v[30:31]
	v_mov_b32_dpp v34, v35 row_ror:8 row_mask:0xf bank_mask:0xf
	v_add_f32_e32 v16, v28, v29
	v_add_f32_e32 v17, v30, v31
	v_cndmask_b32_e64 v32, v34, v35, s[6:7]
	v_cndmask_b32_e64 v33, v35, v34, s[6:7]
	v_cndmask_b32_e64 v18, v16, v17, s[6:7]
	v_cndmask_b32_e64 v19, v17, v16, s[6:7]
	v_pk_add_f32 v[8:9], v[32:33], v[38:39] neg_lo:[1,1] neg_hi:[1,1]
	s_nop 0
	v_add_f32_dpp v36, v18, v19 row_ror:8 row_mask:0xf bank_mask:0xf bound_ctrl:1
	ds_write_b32 v13, v36 offset:512
	s_waitcnt lgkmcnt(9)
	ds_read_b128 v[100:103], v10 offset:1280
	ds_read_b64 v[120:121], v11 offset:1280
	ds_read_b128 v[112:115], v10 offset:13568
	ds_read_b128 v[108:111], v10 offset:9472
	ds_read_b128 v[104:107], v10 offset:5376
	ds_read_b128 v[116:119], v10 offset:17664
	v_pk_mul_f32 v[16:17], v[0:1], v[52:53]
	v_pk_mul_f32 v[18:19], v[4:5], v[52:53]
	v_pk_fma_f32 v[16:17], v[2:3], v[54:55], v[16:17]
	v_pk_fma_f32 v[18:19], v[6:7], v[54:55], v[18:19]
	v_pk_mul_f32 v[14:15], v[72:73], s[4:5] op_sel_hi:[1,0]
	v_pk_mul_f32 v[20:21], v[64:65], v[14:15] op_sel_hi:[1,0]
	v_pk_mul_f32 v[22:23], v[66:67], v[14:15] op_sel_hi:[1,0]
	v_add_f32_e32 v32, v16, v17
	v_add_f32_e32 v33, v18, v19
	v_pk_mul_f32 v[24:25], v[64:65], v[14:15] op_sel:[0,1] op_sel_hi:[1,1]
	v_pk_mul_f32 v[26:27], v[66:67], v[14:15] op_sel:[0,1] op_sel_hi:[1,1]
	v_cndmask_b32_e64 v34, v32, v33, s[6:7]
	v_cndmask_b32_e64 v35, v33, v32, s[6:7]
	v_pk_mul_f32 v[38:39], v[14:15], v[130:131] op_sel:[0,1] op_sel_hi:[1,1]
	v_pk_fma_f32 v[20:21], v[60:61], v[8:9], v[20:21] op_sel_hi:[1,0,1]
	v_add_f32_dpp v35, v34, v35 row_ror:8 row_mask:0xf bank_mask:0xf bound_ctrl:1
	v_pk_fma_f32 v[22:23], v[62:63], v[8:9], v[22:23] op_sel_hi:[1,0,1]
	v_pk_fma_f32 v[24:25], v[60:61], v[8:9], v[24:25] op_sel:[0,1,0] op_sel_hi:[1,1,1]
	v_pk_fma_f32 v[26:27], v[62:63], v[8:9], v[26:27] op_sel:[0,1,0] op_sel_hi:[1,1,1]
	v_add_f32_dpp v35, v35, v35 quad_perm:[1,0,3,2] row_mask:0xf bank_mask:0xf bound_ctrl:1
	v_pk_fma_f32 v[0:1], v[0:1], v[56:57], v[20:21]
	v_pk_fma_f32 v[2:3], v[2:3], v[58:59], v[22:23]
	v_pk_fma_f32 v[4:5], v[4:5], v[56:57], v[24:25]
	v_add_f32_dpp v35, v35, v35 quad_perm:[2,3,0,1] row_mask:0xf bank_mask:0xf bound_ctrl:1
	v_pk_fma_f32 v[6:7], v[6:7], v[58:59], v[26:27]
	v_pk_mul_f32 v[28:29], v[0:1], v[68:69]
	v_pk_fma_f32 v[38:39], v[8:9], v[130:131], v[38:39] op_sel_hi:[1,0,1]
	v_add_f32_dpp v35, v35, v35 row_half_mirror row_mask:0xf bank_mask:0xf bound_ctrl:1
	v_pk_mul_f32 v[30:31], v[4:5], v[68:69]
	v_pk_fma_f32 v[28:29], v[2:3], v[70:71], v[28:29]
	v_pk_fma_f32 v[30:31], v[6:7], v[70:71], v[30:31]
	v_mov_b32_dpp v34, v35 row_ror:8 row_mask:0xf bank_mask:0xf
	v_add_f32_e32 v16, v28, v29
	v_add_f32_e32 v17, v30, v31
	v_cndmask_b32_e64 v32, v34, v35, s[6:7]
	v_cndmask_b32_e64 v33, v35, v34, s[6:7]
	v_cndmask_b32_e64 v18, v16, v17, s[6:7]
	v_cndmask_b32_e64 v19, v17, v16, s[6:7]
	v_pk_add_f32 v[8:9], v[32:33], v[38:39] neg_lo:[1,1] neg_hi:[1,1]
	s_nop 0
	v_add_f32_dpp v36, v18, v19 row_ror:8 row_mask:0xf bank_mask:0xf bound_ctrl:1
	ds_write_b32 v13, v36 offset:768
	s_waitcnt lgkmcnt(8)
	ds_read_b128 v[52:55], v10 offset:1536
	ds_read_b64 v[72:73], v11 offset:1536
	ds_read_b128 v[64:67], v10 offset:13824
	ds_read_b128 v[60:63], v10 offset:9728
	ds_read_b128 v[56:59], v10 offset:5632
	ds_read_b128 v[68:71], v10 offset:17920
	ds_read_b128 v[128:131], v12 offset:48
	v_pk_mul_f32 v[16:17], v[0:1], v[76:77]
	v_pk_mul_f32 v[18:19], v[4:5], v[76:77]
	v_pk_fma_f32 v[16:17], v[2:3], v[78:79], v[16:17]
	v_pk_fma_f32 v[18:19], v[6:7], v[78:79], v[18:19]
	v_pk_mul_f32 v[14:15], v[96:97], s[4:5] op_sel_hi:[1,0]
	v_pk_mul_f32 v[20:21], v[88:89], v[14:15] op_sel_hi:[1,0]
	v_pk_mul_f32 v[22:23], v[90:91], v[14:15] op_sel_hi:[1,0]
	v_add_f32_e32 v32, v16, v17
	v_add_f32_e32 v33, v18, v19
	v_pk_mul_f32 v[24:25], v[88:89], v[14:15] op_sel:[0,1] op_sel_hi:[1,1]
	v_pk_mul_f32 v[26:27], v[90:91], v[14:15] op_sel:[0,1] op_sel_hi:[1,1]
	v_cndmask_b32_e64 v34, v32, v33, s[6:7]
	v_cndmask_b32_e64 v35, v33, v32, s[6:7]
	v_pk_mul_f32 v[38:39], v[14:15], v[124:125] op_sel:[0,1] op_sel_hi:[1,1]
	v_pk_fma_f32 v[20:21], v[84:85], v[8:9], v[20:21] op_sel_hi:[1,0,1]
	v_add_f32_dpp v35, v34, v35 row_ror:8 row_mask:0xf bank_mask:0xf bound_ctrl:1
	v_pk_fma_f32 v[22:23], v[86:87], v[8:9], v[22:23] op_sel_hi:[1,0,1]
	v_pk_fma_f32 v[24:25], v[84:85], v[8:9], v[24:25] op_sel:[0,1,0] op_sel_hi:[1,1,1]
	v_pk_fma_f32 v[26:27], v[86:87], v[8:9], v[26:27] op_sel:[0,1,0] op_sel_hi:[1,1,1]
	v_add_f32_dpp v35, v35, v35 quad_perm:[1,0,3,2] row_mask:0xf bank_mask:0xf bound_ctrl:1
	v_pk_fma_f32 v[0:1], v[0:1], v[80:81], v[20:21]
	v_pk_fma_f32 v[2:3], v[2:3], v[82:83], v[22:23]
	v_pk_fma_f32 v[4:5], v[4:5], v[80:81], v[24:25]
	v_add_f32_dpp v35, v35, v35 quad_perm:[2,3,0,1] row_mask:0xf bank_mask:0xf bound_ctrl:1
	v_pk_fma_f32 v[6:7], v[6:7], v[82:83], v[26:27]
	v_pk_mul_f32 v[28:29], v[0:1], v[92:93]
	v_pk_fma_f32 v[38:39], v[8:9], v[124:125], v[38:39] op_sel_hi:[1,0,1]
	v_add_f32_dpp v35, v35, v35 row_half_mirror row_mask:0xf bank_mask:0xf bound_ctrl:1
	v_pk_mul_f32 v[30:31], v[4:5], v[92:93]
	v_pk_fma_f32 v[28:29], v[2:3], v[94:95], v[28:29]
	v_pk_fma_f32 v[30:31], v[6:7], v[94:95], v[30:31]
	v_mov_b32_dpp v34, v35 row_ror:8 row_mask:0xf bank_mask:0xf
	v_add_f32_e32 v16, v28, v29
	v_add_f32_e32 v17, v30, v31
	v_cndmask_b32_e64 v32, v34, v35, s[6:7]
	v_cndmask_b32_e64 v33, v35, v34, s[6:7]
	v_cndmask_b32_e64 v18, v16, v17, s[6:7]
	v_cndmask_b32_e64 v19, v17, v16, s[6:7]
	v_pk_add_f32 v[8:9], v[32:33], v[38:39] neg_lo:[1,1] neg_hi:[1,1]
	s_nop 0
	v_add_f32_dpp v36, v18, v19 row_ror:8 row_mask:0xf bank_mask:0xf bound_ctrl:1
	ds_write_b32 v13, v36 offset:1024
	s_waitcnt lgkmcnt(9)
	ds_read_b128 v[76:79], v10 offset:1792
	ds_read_b64 v[96:97], v11 offset:1792
	ds_read_b128 v[88:91], v10 offset:14080
	ds_read_b128 v[84:87], v10 offset:9984
	ds_read_b128 v[80:83], v10 offset:5888
	ds_read_b128 v[92:95], v10 offset:18176
	v_pk_mul_f32 v[16:17], v[0:1], v[100:101]
	v_pk_mul_f32 v[18:19], v[4:5], v[100:101]
	v_pk_fma_f32 v[16:17], v[2:3], v[102:103], v[16:17]
	v_pk_fma_f32 v[18:19], v[6:7], v[102:103], v[18:19]
	v_pk_mul_f32 v[14:15], v[120:121], s[4:5] op_sel_hi:[1,0]
	v_pk_mul_f32 v[20:21], v[112:113], v[14:15] op_sel_hi:[1,0]
	v_pk_mul_f32 v[22:23], v[114:115], v[14:15] op_sel_hi:[1,0]
	v_add_f32_e32 v32, v16, v17
	v_add_f32_e32 v33, v18, v19
	v_pk_mul_f32 v[24:25], v[112:113], v[14:15] op_sel:[0,1] op_sel_hi:[1,1]
	v_pk_mul_f32 v[26:27], v[114:115], v[14:15] op_sel:[0,1] op_sel_hi:[1,1]
	v_cndmask_b32_e64 v34, v32, v33, s[6:7]
	v_cndmask_b32_e64 v35, v33, v32, s[6:7]
	v_pk_mul_f32 v[38:39], v[14:15], v[126:127] op_sel:[0,1] op_sel_hi:[1,1]
	v_pk_fma_f32 v[20:21], v[108:109], v[8:9], v[20:21] op_sel_hi:[1,0,1]
	v_add_f32_dpp v35, v34, v35 row_ror:8 row_mask:0xf bank_mask:0xf bound_ctrl:1
	v_pk_fma_f32 v[22:23], v[110:111], v[8:9], v[22:23] op_sel_hi:[1,0,1]
	v_pk_fma_f32 v[24:25], v[108:109], v[8:9], v[24:25] op_sel:[0,1,0] op_sel_hi:[1,1,1]
	v_pk_fma_f32 v[26:27], v[110:111], v[8:9], v[26:27] op_sel:[0,1,0] op_sel_hi:[1,1,1]
	v_add_f32_dpp v35, v35, v35 quad_perm:[1,0,3,2] row_mask:0xf bank_mask:0xf bound_ctrl:1
	v_pk_fma_f32 v[0:1], v[0:1], v[104:105], v[20:21]
	v_pk_fma_f32 v[2:3], v[2:3], v[106:107], v[22:23]
	v_pk_fma_f32 v[4:5], v[4:5], v[104:105], v[24:25]
	v_add_f32_dpp v35, v35, v35 quad_perm:[2,3,0,1] row_mask:0xf bank_mask:0xf bound_ctrl:1
	v_pk_fma_f32 v[6:7], v[6:7], v[106:107], v[26:27]
	v_pk_mul_f32 v[28:29], v[0:1], v[116:117]
	v_pk_fma_f32 v[38:39], v[8:9], v[126:127], v[38:39] op_sel_hi:[1,0,1]
	v_add_f32_dpp v35, v35, v35 row_half_mirror row_mask:0xf bank_mask:0xf bound_ctrl:1
	v_pk_mul_f32 v[30:31], v[4:5], v[116:117]
	v_pk_fma_f32 v[28:29], v[2:3], v[118:119], v[28:29]
	v_pk_fma_f32 v[30:31], v[6:7], v[118:119], v[30:31]
	v_mov_b32_dpp v34, v35 row_ror:8 row_mask:0xf bank_mask:0xf
	v_add_f32_e32 v16, v28, v29
	v_add_f32_e32 v17, v30, v31
	v_cndmask_b32_e64 v32, v34, v35, s[6:7]
	v_cndmask_b32_e64 v33, v35, v34, s[6:7]
	v_cndmask_b32_e64 v18, v16, v17, s[6:7]
	v_cndmask_b32_e64 v19, v17, v16, s[6:7]
	v_pk_add_f32 v[8:9], v[32:33], v[38:39] neg_lo:[1,1] neg_hi:[1,1]
	s_nop 0
	v_add_f32_dpp v36, v18, v19 row_ror:8 row_mask:0xf bank_mask:0xf bound_ctrl:1
	ds_write_b32 v13, v36 offset:1280
	s_waitcnt lgkmcnt(8)
	ds_read_b128 v[100:103], v10 offset:2048
	ds_read_b64 v[120:121], v11 offset:2048
	ds_read_b128 v[112:115], v10 offset:14336
	ds_read_b128 v[108:111], v10 offset:10240
	ds_read_b128 v[104:107], v10 offset:6144
	ds_read_b128 v[116:119], v10 offset:18432
	ds_read_b128 v[124:127], v12 offset:64
	v_pk_mul_f32 v[16:17], v[0:1], v[52:53]
	v_pk_mul_f32 v[18:19], v[4:5], v[52:53]
	v_pk_fma_f32 v[16:17], v[2:3], v[54:55], v[16:17]
	v_pk_fma_f32 v[18:19], v[6:7], v[54:55], v[18:19]
	v_pk_mul_f32 v[14:15], v[72:73], s[4:5] op_sel_hi:[1,0]
	v_pk_mul_f32 v[20:21], v[64:65], v[14:15] op_sel_hi:[1,0]
	v_pk_mul_f32 v[22:23], v[66:67], v[14:15] op_sel_hi:[1,0]
	v_add_f32_e32 v32, v16, v17
	v_add_f32_e32 v33, v18, v19
	v_pk_mul_f32 v[24:25], v[64:65], v[14:15] op_sel:[0,1] op_sel_hi:[1,1]
	v_pk_mul_f32 v[26:27], v[66:67], v[14:15] op_sel:[0,1] op_sel_hi:[1,1]
	v_cndmask_b32_e64 v34, v32, v33, s[6:7]
	v_cndmask_b32_e64 v35, v33, v32, s[6:7]
	v_pk_mul_f32 v[38:39], v[14:15], v[128:129] op_sel:[0,1] op_sel_hi:[1,1]
	v_pk_fma_f32 v[20:21], v[60:61], v[8:9], v[20:21] op_sel_hi:[1,0,1]
	v_add_f32_dpp v35, v34, v35 row_ror:8 row_mask:0xf bank_mask:0xf bound_ctrl:1
	v_pk_fma_f32 v[22:23], v[62:63], v[8:9], v[22:23] op_sel_hi:[1,0,1]
	v_pk_fma_f32 v[24:25], v[60:61], v[8:9], v[24:25] op_sel:[0,1,0] op_sel_hi:[1,1,1]
	v_pk_fma_f32 v[26:27], v[62:63], v[8:9], v[26:27] op_sel:[0,1,0] op_sel_hi:[1,1,1]
	v_add_f32_dpp v35, v35, v35 quad_perm:[1,0,3,2] row_mask:0xf bank_mask:0xf bound_ctrl:1
	v_pk_fma_f32 v[0:1], v[0:1], v[56:57], v[20:21]
	v_pk_fma_f32 v[2:3], v[2:3], v[58:59], v[22:23]
	v_pk_fma_f32 v[4:5], v[4:5], v[56:57], v[24:25]
	v_add_f32_dpp v35, v35, v35 quad_perm:[2,3,0,1] row_mask:0xf bank_mask:0xf bound_ctrl:1
	v_pk_fma_f32 v[6:7], v[6:7], v[58:59], v[26:27]
	v_pk_mul_f32 v[28:29], v[0:1], v[68:69]
	v_pk_fma_f32 v[38:39], v[8:9], v[128:129], v[38:39] op_sel_hi:[1,0,1]
	v_add_f32_dpp v35, v35, v35 row_half_mirror row_mask:0xf bank_mask:0xf bound_ctrl:1
	v_pk_mul_f32 v[30:31], v[4:5], v[68:69]
	v_pk_fma_f32 v[28:29], v[2:3], v[70:71], v[28:29]
	v_pk_fma_f32 v[30:31], v[6:7], v[70:71], v[30:31]
	v_mov_b32_dpp v34, v35 row_ror:8 row_mask:0xf bank_mask:0xf
	v_add_f32_e32 v16, v28, v29
	v_add_f32_e32 v17, v30, v31
	v_cndmask_b32_e64 v32, v34, v35, s[6:7]
	v_cndmask_b32_e64 v33, v35, v34, s[6:7]
	v_cndmask_b32_e64 v18, v16, v17, s[6:7]
	v_cndmask_b32_e64 v19, v17, v16, s[6:7]
	v_pk_add_f32 v[8:9], v[32:33], v[38:39] neg_lo:[1,1] neg_hi:[1,1]
	s_nop 0
	v_add_f32_dpp v36, v18, v19 row_ror:8 row_mask:0xf bank_mask:0xf bound_ctrl:1
	ds_write_b32 v13, v36 offset:1536
	s_waitcnt lgkmcnt(9)
	ds_read_b128 v[52:55], v10 offset:2304
	ds_read_b64 v[72:73], v11 offset:2304
	ds_read_b128 v[64:67], v10 offset:14592
	ds_read_b128 v[60:63], v10 offset:10496
	ds_read_b128 v[56:59], v10 offset:6400
	ds_read_b128 v[68:71], v10 offset:18688
	v_pk_mul_f32 v[16:17], v[0:1], v[76:77]
	v_pk_mul_f32 v[18:19], v[4:5], v[76:77]
	v_pk_fma_f32 v[16:17], v[2:3], v[78:79], v[16:17]
	v_pk_fma_f32 v[18:19], v[6:7], v[78:79], v[18:19]
	v_pk_mul_f32 v[14:15], v[96:97], s[4:5] op_sel_hi:[1,0]
	v_pk_mul_f32 v[20:21], v[88:89], v[14:15] op_sel_hi:[1,0]
	v_pk_mul_f32 v[22:23], v[90:91], v[14:15] op_sel_hi:[1,0]
	v_add_f32_e32 v32, v16, v17
	v_add_f32_e32 v33, v18, v19
	v_pk_mul_f32 v[24:25], v[88:89], v[14:15] op_sel:[0,1] op_sel_hi:[1,1]
	v_pk_mul_f32 v[26:27], v[90:91], v[14:15] op_sel:[0,1] op_sel_hi:[1,1]
	v_cndmask_b32_e64 v34, v32, v33, s[6:7]
	v_cndmask_b32_e64 v35, v33, v32, s[6:7]
	v_pk_mul_f32 v[38:39], v[14:15], v[130:131] op_sel:[0,1] op_sel_hi:[1,1]
	v_pk_fma_f32 v[20:21], v[84:85], v[8:9], v[20:21] op_sel_hi:[1,0,1]
	v_add_f32_dpp v35, v34, v35 row_ror:8 row_mask:0xf bank_mask:0xf bound_ctrl:1
	v_pk_fma_f32 v[22:23], v[86:87], v[8:9], v[22:23] op_sel_hi:[1,0,1]
	v_pk_fma_f32 v[24:25], v[84:85], v[8:9], v[24:25] op_sel:[0,1,0] op_sel_hi:[1,1,1]
	v_pk_fma_f32 v[26:27], v[86:87], v[8:9], v[26:27] op_sel:[0,1,0] op_sel_hi:[1,1,1]
	v_add_f32_dpp v35, v35, v35 quad_perm:[1,0,3,2] row_mask:0xf bank_mask:0xf bound_ctrl:1
	v_pk_fma_f32 v[0:1], v[0:1], v[80:81], v[20:21]
	v_pk_fma_f32 v[2:3], v[2:3], v[82:83], v[22:23]
	v_pk_fma_f32 v[4:5], v[4:5], v[80:81], v[24:25]
	v_add_f32_dpp v35, v35, v35 quad_perm:[2,3,0,1] row_mask:0xf bank_mask:0xf bound_ctrl:1
	v_pk_fma_f32 v[6:7], v[6:7], v[82:83], v[26:27]
	v_pk_mul_f32 v[28:29], v[0:1], v[92:93]
	v_pk_fma_f32 v[38:39], v[8:9], v[130:131], v[38:39] op_sel_hi:[1,0,1]
	v_add_f32_dpp v35, v35, v35 row_half_mirror row_mask:0xf bank_mask:0xf bound_ctrl:1
	v_pk_mul_f32 v[30:31], v[4:5], v[92:93]
	v_pk_fma_f32 v[28:29], v[2:3], v[94:95], v[28:29]
	v_pk_fma_f32 v[30:31], v[6:7], v[94:95], v[30:31]
	v_mov_b32_dpp v34, v35 row_ror:8 row_mask:0xf bank_mask:0xf
	v_add_f32_e32 v16, v28, v29
	v_add_f32_e32 v17, v30, v31
	v_cndmask_b32_e64 v32, v34, v35, s[6:7]
	v_cndmask_b32_e64 v33, v35, v34, s[6:7]
	v_cndmask_b32_e64 v18, v16, v17, s[6:7]
	v_cndmask_b32_e64 v19, v17, v16, s[6:7]
	v_pk_add_f32 v[8:9], v[32:33], v[38:39] neg_lo:[1,1] neg_hi:[1,1]
	s_nop 0
	v_add_f32_dpp v36, v18, v19 row_ror:8 row_mask:0xf bank_mask:0xf bound_ctrl:1
	ds_write_b32 v13, v36 offset:1792
	s_waitcnt lgkmcnt(8)
	ds_read_b128 v[76:79], v10 offset:2560
	ds_read_b64 v[96:97], v11 offset:2560
	ds_read_b128 v[88:91], v10 offset:14848
	ds_read_b128 v[84:87], v10 offset:10752
	ds_read_b128 v[80:83], v10 offset:6656
	ds_read_b128 v[92:95], v10 offset:18944
	ds_read_b128 v[128:131], v12 offset:80
	v_pk_mul_f32 v[16:17], v[0:1], v[100:101]
	v_pk_mul_f32 v[18:19], v[4:5], v[100:101]
	v_pk_fma_f32 v[16:17], v[2:3], v[102:103], v[16:17]
	v_pk_fma_f32 v[18:19], v[6:7], v[102:103], v[18:19]
	v_pk_mul_f32 v[14:15], v[120:121], s[4:5] op_sel_hi:[1,0]
	v_pk_mul_f32 v[20:21], v[112:113], v[14:15] op_sel_hi:[1,0]
	v_pk_mul_f32 v[22:23], v[114:115], v[14:15] op_sel_hi:[1,0]
	v_add_f32_e32 v32, v16, v17
	v_add_f32_e32 v33, v18, v19
	v_pk_mul_f32 v[24:25], v[112:113], v[14:15] op_sel:[0,1] op_sel_hi:[1,1]
	v_pk_mul_f32 v[26:27], v[114:115], v[14:15] op_sel:[0,1] op_sel_hi:[1,1]
	v_cndmask_b32_e64 v34, v32, v33, s[6:7]
	v_cndmask_b32_e64 v35, v33, v32, s[6:7]
	v_pk_mul_f32 v[38:39], v[14:15], v[124:125] op_sel:[0,1] op_sel_hi:[1,1]
	v_pk_fma_f32 v[20:21], v[108:109], v[8:9], v[20:21] op_sel_hi:[1,0,1]
	v_add_f32_dpp v35, v34, v35 row_ror:8 row_mask:0xf bank_mask:0xf bound_ctrl:1
	v_pk_fma_f32 v[22:23], v[110:111], v[8:9], v[22:23] op_sel_hi:[1,0,1]
	v_pk_fma_f32 v[24:25], v[108:109], v[8:9], v[24:25] op_sel:[0,1,0] op_sel_hi:[1,1,1]
	v_pk_fma_f32 v[26:27], v[110:111], v[8:9], v[26:27] op_sel:[0,1,0] op_sel_hi:[1,1,1]
	v_add_f32_dpp v35, v35, v35 quad_perm:[1,0,3,2] row_mask:0xf bank_mask:0xf bound_ctrl:1
	v_pk_fma_f32 v[0:1], v[0:1], v[104:105], v[20:21]
	v_pk_fma_f32 v[2:3], v[2:3], v[106:107], v[22:23]
	v_pk_fma_f32 v[4:5], v[4:5], v[104:105], v[24:25]
	v_add_f32_dpp v35, v35, v35 quad_perm:[2,3,0,1] row_mask:0xf bank_mask:0xf bound_ctrl:1
	v_pk_fma_f32 v[6:7], v[6:7], v[106:107], v[26:27]
	v_pk_mul_f32 v[28:29], v[0:1], v[116:117]
	v_pk_fma_f32 v[38:39], v[8:9], v[124:125], v[38:39] op_sel_hi:[1,0,1]
	v_add_f32_dpp v35, v35, v35 row_half_mirror row_mask:0xf bank_mask:0xf bound_ctrl:1
	v_pk_mul_f32 v[30:31], v[4:5], v[116:117]
	v_pk_fma_f32 v[28:29], v[2:3], v[118:119], v[28:29]
	v_pk_fma_f32 v[30:31], v[6:7], v[118:119], v[30:31]
	v_mov_b32_dpp v34, v35 row_ror:8 row_mask:0xf bank_mask:0xf
	v_add_f32_e32 v16, v28, v29
	v_add_f32_e32 v17, v30, v31
	v_cndmask_b32_e64 v32, v34, v35, s[6:7]
	v_cndmask_b32_e64 v33, v35, v34, s[6:7]
	v_cndmask_b32_e64 v18, v16, v17, s[6:7]
	v_cndmask_b32_e64 v19, v17, v16, s[6:7]
	v_pk_add_f32 v[8:9], v[32:33], v[38:39] neg_lo:[1,1] neg_hi:[1,1]
	s_nop 0
	v_add_f32_dpp v36, v18, v19 row_ror:8 row_mask:0xf bank_mask:0xf bound_ctrl:1
	ds_write_b32 v13, v36 offset:2048
	s_waitcnt lgkmcnt(9)
	ds_read_b128 v[100:103], v10 offset:2816
	ds_read_b64 v[120:121], v11 offset:2816
	ds_read_b128 v[112:115], v10 offset:15104
	ds_read_b128 v[108:111], v10 offset:11008
	ds_read_b128 v[104:107], v10 offset:6912
	ds_read_b128 v[116:119], v10 offset:19200
	v_pk_mul_f32 v[16:17], v[0:1], v[52:53]
	v_pk_mul_f32 v[18:19], v[4:5], v[52:53]
	v_pk_fma_f32 v[16:17], v[2:3], v[54:55], v[16:17]
	v_pk_fma_f32 v[18:19], v[6:7], v[54:55], v[18:19]
	v_pk_mul_f32 v[14:15], v[72:73], s[4:5] op_sel_hi:[1,0]
	v_pk_mul_f32 v[20:21], v[64:65], v[14:15] op_sel_hi:[1,0]
	v_pk_mul_f32 v[22:23], v[66:67], v[14:15] op_sel_hi:[1,0]
	v_add_f32_e32 v32, v16, v17
	v_add_f32_e32 v33, v18, v19
	v_pk_mul_f32 v[24:25], v[64:65], v[14:15] op_sel:[0,1] op_sel_hi:[1,1]
	v_pk_mul_f32 v[26:27], v[66:67], v[14:15] op_sel:[0,1] op_sel_hi:[1,1]
	v_cndmask_b32_e64 v34, v32, v33, s[6:7]
	v_cndmask_b32_e64 v35, v33, v32, s[6:7]
	v_pk_mul_f32 v[38:39], v[14:15], v[126:127] op_sel:[0,1] op_sel_hi:[1,1]
	v_pk_fma_f32 v[20:21], v[60:61], v[8:9], v[20:21] op_sel_hi:[1,0,1]
	v_add_f32_dpp v35, v34, v35 row_ror:8 row_mask:0xf bank_mask:0xf bound_ctrl:1
	v_pk_fma_f32 v[22:23], v[62:63], v[8:9], v[22:23] op_sel_hi:[1,0,1]
	v_pk_fma_f32 v[24:25], v[60:61], v[8:9], v[24:25] op_sel:[0,1,0] op_sel_hi:[1,1,1]
	v_pk_fma_f32 v[26:27], v[62:63], v[8:9], v[26:27] op_sel:[0,1,0] op_sel_hi:[1,1,1]
	v_add_f32_dpp v35, v35, v35 quad_perm:[1,0,3,2] row_mask:0xf bank_mask:0xf bound_ctrl:1
	v_pk_fma_f32 v[0:1], v[0:1], v[56:57], v[20:21]
	v_pk_fma_f32 v[2:3], v[2:3], v[58:59], v[22:23]
	v_pk_fma_f32 v[4:5], v[4:5], v[56:57], v[24:25]
	v_add_f32_dpp v35, v35, v35 quad_perm:[2,3,0,1] row_mask:0xf bank_mask:0xf bound_ctrl:1
	v_pk_fma_f32 v[6:7], v[6:7], v[58:59], v[26:27]
	v_pk_mul_f32 v[28:29], v[0:1], v[68:69]
	v_pk_fma_f32 v[38:39], v[8:9], v[126:127], v[38:39] op_sel_hi:[1,0,1]
	v_add_f32_dpp v35, v35, v35 row_half_mirror row_mask:0xf bank_mask:0xf bound_ctrl:1
	v_pk_mul_f32 v[30:31], v[4:5], v[68:69]
	v_pk_fma_f32 v[28:29], v[2:3], v[70:71], v[28:29]
	v_pk_fma_f32 v[30:31], v[6:7], v[70:71], v[30:31]
	v_mov_b32_dpp v34, v35 row_ror:8 row_mask:0xf bank_mask:0xf
	v_add_f32_e32 v16, v28, v29
	v_add_f32_e32 v17, v30, v31
	v_cndmask_b32_e64 v32, v34, v35, s[6:7]
	v_cndmask_b32_e64 v33, v35, v34, s[6:7]
	v_cndmask_b32_e64 v18, v16, v17, s[6:7]
	v_cndmask_b32_e64 v19, v17, v16, s[6:7]
	v_pk_add_f32 v[8:9], v[32:33], v[38:39] neg_lo:[1,1] neg_hi:[1,1]
	s_nop 0
	v_add_f32_dpp v36, v18, v19 row_ror:8 row_mask:0xf bank_mask:0xf bound_ctrl:1
	ds_write_b32 v13, v36 offset:2304
	s_waitcnt lgkmcnt(8)
	ds_read_b128 v[52:55], v10 offset:3072
	ds_read_b64 v[72:73], v11 offset:3072
	ds_read_b128 v[64:67], v10 offset:15360
	ds_read_b128 v[60:63], v10 offset:11264
	ds_read_b128 v[56:59], v10 offset:7168
	ds_read_b128 v[68:71], v10 offset:19456
	ds_read_b128 v[124:127], v12 offset:96
	v_pk_mul_f32 v[16:17], v[0:1], v[76:77]
	v_pk_mul_f32 v[18:19], v[4:5], v[76:77]
	v_pk_fma_f32 v[16:17], v[2:3], v[78:79], v[16:17]
	v_pk_fma_f32 v[18:19], v[6:7], v[78:79], v[18:19]
	v_pk_mul_f32 v[14:15], v[96:97], s[4:5] op_sel_hi:[1,0]
	v_pk_mul_f32 v[20:21], v[88:89], v[14:15] op_sel_hi:[1,0]
	v_pk_mul_f32 v[22:23], v[90:91], v[14:15] op_sel_hi:[1,0]
	v_add_f32_e32 v32, v16, v17
	v_add_f32_e32 v33, v18, v19
	v_pk_mul_f32 v[24:25], v[88:89], v[14:15] op_sel:[0,1] op_sel_hi:[1,1]
	v_pk_mul_f32 v[26:27], v[90:91], v[14:15] op_sel:[0,1] op_sel_hi:[1,1]
	v_cndmask_b32_e64 v34, v32, v33, s[6:7]
	v_cndmask_b32_e64 v35, v33, v32, s[6:7]
	v_pk_mul_f32 v[38:39], v[14:15], v[128:129] op_sel:[0,1] op_sel_hi:[1,1]
	v_pk_fma_f32 v[20:21], v[84:85], v[8:9], v[20:21] op_sel_hi:[1,0,1]
	v_add_f32_dpp v35, v34, v35 row_ror:8 row_mask:0xf bank_mask:0xf bound_ctrl:1
	v_pk_fma_f32 v[22:23], v[86:87], v[8:9], v[22:23] op_sel_hi:[1,0,1]
	v_pk_fma_f32 v[24:25], v[84:85], v[8:9], v[24:25] op_sel:[0,1,0] op_sel_hi:[1,1,1]
	v_pk_fma_f32 v[26:27], v[86:87], v[8:9], v[26:27] op_sel:[0,1,0] op_sel_hi:[1,1,1]
	v_add_f32_dpp v35, v35, v35 quad_perm:[1,0,3,2] row_mask:0xf bank_mask:0xf bound_ctrl:1
	v_pk_fma_f32 v[0:1], v[0:1], v[80:81], v[20:21]
	v_pk_fma_f32 v[2:3], v[2:3], v[82:83], v[22:23]
	v_pk_fma_f32 v[4:5], v[4:5], v[80:81], v[24:25]
	v_add_f32_dpp v35, v35, v35 quad_perm:[2,3,0,1] row_mask:0xf bank_mask:0xf bound_ctrl:1
	v_pk_fma_f32 v[6:7], v[6:7], v[82:83], v[26:27]
	v_pk_mul_f32 v[28:29], v[0:1], v[92:93]
	v_pk_fma_f32 v[38:39], v[8:9], v[128:129], v[38:39] op_sel_hi:[1,0,1]
	v_add_f32_dpp v35, v35, v35 row_half_mirror row_mask:0xf bank_mask:0xf bound_ctrl:1
	v_pk_mul_f32 v[30:31], v[4:5], v[92:93]
	v_pk_fma_f32 v[28:29], v[2:3], v[94:95], v[28:29]
	v_pk_fma_f32 v[30:31], v[6:7], v[94:95], v[30:31]
	v_mov_b32_dpp v34, v35 row_ror:8 row_mask:0xf bank_mask:0xf
	v_add_f32_e32 v16, v28, v29
	v_add_f32_e32 v17, v30, v31
	v_cndmask_b32_e64 v32, v34, v35, s[6:7]
	v_cndmask_b32_e64 v33, v35, v34, s[6:7]
	v_cndmask_b32_e64 v18, v16, v17, s[6:7]
	v_cndmask_b32_e64 v19, v17, v16, s[6:7]
	v_pk_add_f32 v[8:9], v[32:33], v[38:39] neg_lo:[1,1] neg_hi:[1,1]
	s_nop 0
	v_add_f32_dpp v36, v18, v19 row_ror:8 row_mask:0xf bank_mask:0xf bound_ctrl:1
	ds_write_b32 v13, v36 offset:2560
	s_waitcnt lgkmcnt(9)
	ds_read_b128 v[76:79], v10 offset:3328
	ds_read_b64 v[96:97], v11 offset:3328
	ds_read_b128 v[88:91], v10 offset:15616
	ds_read_b128 v[84:87], v10 offset:11520
	ds_read_b128 v[80:83], v10 offset:7424
	ds_read_b128 v[92:95], v10 offset:19712
	v_pk_mul_f32 v[16:17], v[0:1], v[100:101]
	v_pk_mul_f32 v[18:19], v[4:5], v[100:101]
	v_pk_fma_f32 v[16:17], v[2:3], v[102:103], v[16:17]
	v_pk_fma_f32 v[18:19], v[6:7], v[102:103], v[18:19]
	v_pk_mul_f32 v[14:15], v[120:121], s[4:5] op_sel_hi:[1,0]
	v_pk_mul_f32 v[20:21], v[112:113], v[14:15] op_sel_hi:[1,0]
	v_pk_mul_f32 v[22:23], v[114:115], v[14:15] op_sel_hi:[1,0]
	v_add_f32_e32 v32, v16, v17
	v_add_f32_e32 v33, v18, v19
	v_pk_mul_f32 v[24:25], v[112:113], v[14:15] op_sel:[0,1] op_sel_hi:[1,1]
	v_pk_mul_f32 v[26:27], v[114:115], v[14:15] op_sel:[0,1] op_sel_hi:[1,1]
	v_cndmask_b32_e64 v34, v32, v33, s[6:7]
	v_cndmask_b32_e64 v35, v33, v32, s[6:7]
	v_pk_mul_f32 v[38:39], v[14:15], v[130:131] op_sel:[0,1] op_sel_hi:[1,1]
	v_pk_fma_f32 v[20:21], v[108:109], v[8:9], v[20:21] op_sel_hi:[1,0,1]
	v_add_f32_dpp v35, v34, v35 row_ror:8 row_mask:0xf bank_mask:0xf bound_ctrl:1
	v_pk_fma_f32 v[22:23], v[110:111], v[8:9], v[22:23] op_sel_hi:[1,0,1]
	v_pk_fma_f32 v[24:25], v[108:109], v[8:9], v[24:25] op_sel:[0,1,0] op_sel_hi:[1,1,1]
	v_pk_fma_f32 v[26:27], v[110:111], v[8:9], v[26:27] op_sel:[0,1,0] op_sel_hi:[1,1,1]
	v_add_f32_dpp v35, v35, v35 quad_perm:[1,0,3,2] row_mask:0xf bank_mask:0xf bound_ctrl:1
	v_pk_fma_f32 v[0:1], v[0:1], v[104:105], v[20:21]
	v_pk_fma_f32 v[2:3], v[2:3], v[106:107], v[22:23]
	v_pk_fma_f32 v[4:5], v[4:5], v[104:105], v[24:25]
	v_add_f32_dpp v35, v35, v35 quad_perm:[2,3,0,1] row_mask:0xf bank_mask:0xf bound_ctrl:1
	v_pk_fma_f32 v[6:7], v[6:7], v[106:107], v[26:27]
	v_pk_mul_f32 v[28:29], v[0:1], v[116:117]
	v_pk_fma_f32 v[38:39], v[8:9], v[130:131], v[38:39] op_sel_hi:[1,0,1]
	v_add_f32_dpp v35, v35, v35 row_half_mirror row_mask:0xf bank_mask:0xf bound_ctrl:1
	v_pk_mul_f32 v[30:31], v[4:5], v[116:117]
	v_pk_fma_f32 v[28:29], v[2:3], v[118:119], v[28:29]
	v_pk_fma_f32 v[30:31], v[6:7], v[118:119], v[30:31]
	v_mov_b32_dpp v34, v35 row_ror:8 row_mask:0xf bank_mask:0xf
	v_add_f32_e32 v16, v28, v29
	v_add_f32_e32 v17, v30, v31
	v_cndmask_b32_e64 v32, v34, v35, s[6:7]
	v_cndmask_b32_e64 v33, v35, v34, s[6:7]
	v_cndmask_b32_e64 v18, v16, v17, s[6:7]
	v_cndmask_b32_e64 v19, v17, v16, s[6:7]
	v_pk_add_f32 v[8:9], v[32:33], v[38:39] neg_lo:[1,1] neg_hi:[1,1]
	s_nop 0
	v_add_f32_dpp v36, v18, v19 row_ror:8 row_mask:0xf bank_mask:0xf bound_ctrl:1
	ds_write_b32 v13, v36 offset:2816
	s_waitcnt lgkmcnt(8)
	ds_read_b128 v[100:103], v10 offset:3584
	ds_read_b64 v[120:121], v11 offset:3584
	ds_read_b128 v[112:115], v10 offset:15872
	ds_read_b128 v[108:111], v10 offset:11776
	ds_read_b128 v[104:107], v10 offset:7680
	ds_read_b128 v[116:119], v10 offset:19968
	ds_read_b128 v[128:131], v12 offset:112
	v_pk_mul_f32 v[16:17], v[0:1], v[52:53]
	v_pk_mul_f32 v[18:19], v[4:5], v[52:53]
	v_pk_fma_f32 v[16:17], v[2:3], v[54:55], v[16:17]
	v_pk_fma_f32 v[18:19], v[6:7], v[54:55], v[18:19]
	v_pk_mul_f32 v[14:15], v[72:73], s[4:5] op_sel_hi:[1,0]
	v_pk_mul_f32 v[20:21], v[64:65], v[14:15] op_sel_hi:[1,0]
	v_pk_mul_f32 v[22:23], v[66:67], v[14:15] op_sel_hi:[1,0]
	v_add_f32_e32 v32, v16, v17
	v_add_f32_e32 v33, v18, v19
	v_pk_mul_f32 v[24:25], v[64:65], v[14:15] op_sel:[0,1] op_sel_hi:[1,1]
	v_pk_mul_f32 v[26:27], v[66:67], v[14:15] op_sel:[0,1] op_sel_hi:[1,1]
	v_cndmask_b32_e64 v34, v32, v33, s[6:7]
	v_cndmask_b32_e64 v35, v33, v32, s[6:7]
	v_pk_mul_f32 v[38:39], v[14:15], v[124:125] op_sel:[0,1] op_sel_hi:[1,1]
	v_pk_fma_f32 v[20:21], v[60:61], v[8:9], v[20:21] op_sel_hi:[1,0,1]
	v_add_f32_dpp v35, v34, v35 row_ror:8 row_mask:0xf bank_mask:0xf bound_ctrl:1
	v_pk_fma_f32 v[22:23], v[62:63], v[8:9], v[22:23] op_sel_hi:[1,0,1]
	v_pk_fma_f32 v[24:25], v[60:61], v[8:9], v[24:25] op_sel:[0,1,0] op_sel_hi:[1,1,1]
	v_pk_fma_f32 v[26:27], v[62:63], v[8:9], v[26:27] op_sel:[0,1,0] op_sel_hi:[1,1,1]
	v_add_f32_dpp v35, v35, v35 quad_perm:[1,0,3,2] row_mask:0xf bank_mask:0xf bound_ctrl:1
	v_pk_fma_f32 v[0:1], v[0:1], v[56:57], v[20:21]
	v_pk_fma_f32 v[2:3], v[2:3], v[58:59], v[22:23]
	v_pk_fma_f32 v[4:5], v[4:5], v[56:57], v[24:25]
	v_add_f32_dpp v35, v35, v35 quad_perm:[2,3,0,1] row_mask:0xf bank_mask:0xf bound_ctrl:1
	v_pk_fma_f32 v[6:7], v[6:7], v[58:59], v[26:27]
	v_pk_mul_f32 v[28:29], v[0:1], v[68:69]
	v_pk_fma_f32 v[38:39], v[8:9], v[124:125], v[38:39] op_sel_hi:[1,0,1]
	v_add_f32_dpp v35, v35, v35 row_half_mirror row_mask:0xf bank_mask:0xf bound_ctrl:1
	v_pk_mul_f32 v[30:31], v[4:5], v[68:69]
	v_pk_fma_f32 v[28:29], v[2:3], v[70:71], v[28:29]
	v_pk_fma_f32 v[30:31], v[6:7], v[70:71], v[30:31]
	v_mov_b32_dpp v34, v35 row_ror:8 row_mask:0xf bank_mask:0xf
	v_add_f32_e32 v16, v28, v29
	v_add_f32_e32 v17, v30, v31
	v_cndmask_b32_e64 v32, v34, v35, s[6:7]
	v_cndmask_b32_e64 v33, v35, v34, s[6:7]
	v_cndmask_b32_e64 v18, v16, v17, s[6:7]
	v_cndmask_b32_e64 v19, v17, v16, s[6:7]
	v_pk_add_f32 v[8:9], v[32:33], v[38:39] neg_lo:[1,1] neg_hi:[1,1]
	s_nop 0
	v_add_f32_dpp v36, v18, v19 row_ror:8 row_mask:0xf bank_mask:0xf bound_ctrl:1
	ds_write_b32 v13, v36 offset:3072
	s_waitcnt lgkmcnt(9)
	ds_read_b128 v[52:55], v10 offset:3840
	ds_read_b64 v[72:73], v11 offset:3840
	ds_read_b128 v[64:67], v10 offset:16128
	ds_read_b128 v[60:63], v10 offset:12032
	ds_read_b128 v[56:59], v10 offset:7936
	ds_read_b128 v[68:71], v10 offset:20224
	v_pk_mul_f32 v[16:17], v[0:1], v[76:77]
	v_pk_mul_f32 v[18:19], v[4:5], v[76:77]
	v_pk_fma_f32 v[16:17], v[2:3], v[78:79], v[16:17]
	v_pk_fma_f32 v[18:19], v[6:7], v[78:79], v[18:19]
	v_pk_mul_f32 v[14:15], v[96:97], s[4:5] op_sel_hi:[1,0]
	v_pk_mul_f32 v[20:21], v[88:89], v[14:15] op_sel_hi:[1,0]
	v_pk_mul_f32 v[22:23], v[90:91], v[14:15] op_sel_hi:[1,0]
	v_add_f32_e32 v32, v16, v17
	v_add_f32_e32 v33, v18, v19
	v_pk_mul_f32 v[24:25], v[88:89], v[14:15] op_sel:[0,1] op_sel_hi:[1,1]
	v_pk_mul_f32 v[26:27], v[90:91], v[14:15] op_sel:[0,1] op_sel_hi:[1,1]
	v_cndmask_b32_e64 v34, v32, v33, s[6:7]
	v_cndmask_b32_e64 v35, v33, v32, s[6:7]
	v_pk_mul_f32 v[38:39], v[14:15], v[126:127] op_sel:[0,1] op_sel_hi:[1,1]
	v_pk_fma_f32 v[20:21], v[84:85], v[8:9], v[20:21] op_sel_hi:[1,0,1]
	v_add_f32_dpp v35, v34, v35 row_ror:8 row_mask:0xf bank_mask:0xf bound_ctrl:1
	v_pk_fma_f32 v[22:23], v[86:87], v[8:9], v[22:23] op_sel_hi:[1,0,1]
	v_pk_fma_f32 v[24:25], v[84:85], v[8:9], v[24:25] op_sel:[0,1,0] op_sel_hi:[1,1,1]
	v_pk_fma_f32 v[26:27], v[86:87], v[8:9], v[26:27] op_sel:[0,1,0] op_sel_hi:[1,1,1]
	v_add_f32_dpp v35, v35, v35 quad_perm:[1,0,3,2] row_mask:0xf bank_mask:0xf bound_ctrl:1
	v_pk_fma_f32 v[0:1], v[0:1], v[80:81], v[20:21]
	v_pk_fma_f32 v[2:3], v[2:3], v[82:83], v[22:23]
	v_pk_fma_f32 v[4:5], v[4:5], v[80:81], v[24:25]
	v_add_f32_dpp v35, v35, v35 quad_perm:[2,3,0,1] row_mask:0xf bank_mask:0xf bound_ctrl:1
	v_pk_fma_f32 v[6:7], v[6:7], v[82:83], v[26:27]
	v_pk_mul_f32 v[28:29], v[0:1], v[92:93]
	v_pk_fma_f32 v[38:39], v[8:9], v[126:127], v[38:39] op_sel_hi:[1,0,1]
	v_add_f32_dpp v35, v35, v35 row_half_mirror row_mask:0xf bank_mask:0xf bound_ctrl:1
	v_pk_mul_f32 v[30:31], v[4:5], v[92:93]
	v_pk_fma_f32 v[28:29], v[2:3], v[94:95], v[28:29]
	v_pk_fma_f32 v[30:31], v[6:7], v[94:95], v[30:31]
	v_mov_b32_dpp v34, v35 row_ror:8 row_mask:0xf bank_mask:0xf
	v_add_f32_e32 v16, v28, v29
	v_add_f32_e32 v17, v30, v31
	v_cndmask_b32_e64 v32, v34, v35, s[6:7]
	v_cndmask_b32_e64 v33, v35, v34, s[6:7]
	v_cndmask_b32_e64 v18, v16, v17, s[6:7]
	v_cndmask_b32_e64 v19, v17, v16, s[6:7]
	v_pk_add_f32 v[8:9], v[32:33], v[38:39] neg_lo:[1,1] neg_hi:[1,1]
	s_nop 0
	v_add_f32_dpp v36, v18, v19 row_ror:8 row_mask:0xf bank_mask:0xf bound_ctrl:1
	ds_write_b32 v13, v36 offset:3328
	s_waitcnt lgkmcnt(8)
	v_pk_mul_f32 v[16:17], v[0:1], v[100:101]
	v_pk_mul_f32 v[18:19], v[4:5], v[100:101]
	v_pk_fma_f32 v[16:17], v[2:3], v[102:103], v[16:17]
	v_pk_fma_f32 v[18:19], v[6:7], v[102:103], v[18:19]
	v_pk_mul_f32 v[14:15], v[120:121], s[4:5] op_sel_hi:[1,0]
	v_pk_mul_f32 v[20:21], v[112:113], v[14:15] op_sel_hi:[1,0]
	v_pk_mul_f32 v[22:23], v[114:115], v[14:15] op_sel_hi:[1,0]
	v_add_f32_e32 v32, v16, v17
	v_add_f32_e32 v33, v18, v19
	v_pk_mul_f32 v[24:25], v[112:113], v[14:15] op_sel:[0,1] op_sel_hi:[1,1]
	v_pk_mul_f32 v[26:27], v[114:115], v[14:15] op_sel:[0,1] op_sel_hi:[1,1]
	v_cndmask_b32_e64 v34, v32, v33, s[6:7]
	v_cndmask_b32_e64 v35, v33, v32, s[6:7]
	v_pk_mul_f32 v[38:39], v[14:15], v[128:129] op_sel:[0,1] op_sel_hi:[1,1]
	v_pk_fma_f32 v[20:21], v[108:109], v[8:9], v[20:21] op_sel_hi:[1,0,1]
	v_add_f32_dpp v35, v34, v35 row_ror:8 row_mask:0xf bank_mask:0xf bound_ctrl:1
	v_pk_fma_f32 v[22:23], v[110:111], v[8:9], v[22:23] op_sel_hi:[1,0,1]
	v_pk_fma_f32 v[24:25], v[108:109], v[8:9], v[24:25] op_sel:[0,1,0] op_sel_hi:[1,1,1]
	v_pk_fma_f32 v[26:27], v[110:111], v[8:9], v[26:27] op_sel:[0,1,0] op_sel_hi:[1,1,1]
	v_add_f32_dpp v35, v35, v35 quad_perm:[1,0,3,2] row_mask:0xf bank_mask:0xf bound_ctrl:1
	v_pk_fma_f32 v[0:1], v[0:1], v[104:105], v[20:21]
	v_pk_fma_f32 v[2:3], v[2:3], v[106:107], v[22:23]
	v_pk_fma_f32 v[4:5], v[4:5], v[104:105], v[24:25]
	v_add_f32_dpp v35, v35, v35 quad_perm:[2,3,0,1] row_mask:0xf bank_mask:0xf bound_ctrl:1
	v_pk_fma_f32 v[6:7], v[6:7], v[106:107], v[26:27]
	v_pk_mul_f32 v[28:29], v[0:1], v[116:117]
	v_pk_fma_f32 v[38:39], v[8:9], v[128:129], v[38:39] op_sel_hi:[1,0,1]
	v_add_f32_dpp v35, v35, v35 row_half_mirror row_mask:0xf bank_mask:0xf bound_ctrl:1
	v_pk_mul_f32 v[30:31], v[4:5], v[116:117]
	v_pk_fma_f32 v[28:29], v[2:3], v[118:119], v[28:29]
	v_pk_fma_f32 v[30:31], v[6:7], v[118:119], v[30:31]
	v_mov_b32_dpp v34, v35 row_ror:8 row_mask:0xf bank_mask:0xf
	v_add_f32_e32 v16, v28, v29
	v_add_f32_e32 v17, v30, v31
	v_cndmask_b32_e64 v32, v34, v35, s[6:7]
	v_cndmask_b32_e64 v33, v35, v34, s[6:7]
	v_cndmask_b32_e64 v18, v16, v17, s[6:7]
	v_cndmask_b32_e64 v19, v17, v16, s[6:7]
	v_pk_add_f32 v[8:9], v[32:33], v[38:39] neg_lo:[1,1] neg_hi:[1,1]
	s_nop 0
	v_add_f32_dpp v36, v18, v19 row_ror:8 row_mask:0xf bank_mask:0xf bound_ctrl:1
	ds_write_b32 v13, v36 offset:3584
	s_waitcnt lgkmcnt(2)
	v_pk_mul_f32 v[16:17], v[0:1], v[52:53]
	v_pk_mul_f32 v[18:19], v[4:5], v[52:53]
	v_pk_fma_f32 v[16:17], v[2:3], v[54:55], v[16:17]
	v_pk_fma_f32 v[18:19], v[6:7], v[54:55], v[18:19]
	v_pk_mul_f32 v[14:15], v[72:73], s[4:5] op_sel_hi:[1,0]
	v_pk_mul_f32 v[20:21], v[64:65], v[14:15] op_sel_hi:[1,0]
	v_pk_mul_f32 v[22:23], v[66:67], v[14:15] op_sel_hi:[1,0]
	v_add_f32_e32 v32, v16, v17
	v_add_f32_e32 v33, v18, v19
	v_pk_mul_f32 v[24:25], v[64:65], v[14:15] op_sel:[0,1] op_sel_hi:[1,1]
	v_pk_mul_f32 v[26:27], v[66:67], v[14:15] op_sel:[0,1] op_sel_hi:[1,1]
	v_cndmask_b32_e64 v34, v32, v33, s[6:7]
	v_cndmask_b32_e64 v35, v33, v32, s[6:7]
	v_pk_mul_f32 v[38:39], v[14:15], v[130:131] op_sel:[0,1] op_sel_hi:[1,1]
	v_pk_fma_f32 v[20:21], v[60:61], v[8:9], v[20:21] op_sel_hi:[1,0,1]
	v_add_f32_dpp v35, v34, v35 row_ror:8 row_mask:0xf bank_mask:0xf bound_ctrl:1
	v_pk_fma_f32 v[22:23], v[62:63], v[8:9], v[22:23] op_sel_hi:[1,0,1]
	v_pk_fma_f32 v[24:25], v[60:61], v[8:9], v[24:25] op_sel:[0,1,0] op_sel_hi:[1,1,1]
	v_pk_fma_f32 v[26:27], v[62:63], v[8:9], v[26:27] op_sel:[0,1,0] op_sel_hi:[1,1,1]
	v_add_f32_dpp v35, v35, v35 quad_perm:[1,0,3,2] row_mask:0xf bank_mask:0xf bound_ctrl:1
	v_pk_fma_f32 v[0:1], v[0:1], v[56:57], v[20:21]
	v_pk_fma_f32 v[2:3], v[2:3], v[58:59], v[22:23]
	v_pk_fma_f32 v[4:5], v[4:5], v[56:57], v[24:25]
	v_add_f32_dpp v35, v35, v35 quad_perm:[2,3,0,1] row_mask:0xf bank_mask:0xf bound_ctrl:1
	v_pk_fma_f32 v[6:7], v[6:7], v[58:59], v[26:27]
	v_pk_mul_f32 v[28:29], v[0:1], v[68:69]
	v_pk_fma_f32 v[38:39], v[8:9], v[130:131], v[38:39] op_sel_hi:[1,0,1]
	v_add_f32_dpp v35, v35, v35 row_half_mirror row_mask:0xf bank_mask:0xf bound_ctrl:1
	v_pk_mul_f32 v[30:31], v[4:5], v[68:69]
	v_pk_fma_f32 v[28:29], v[2:3], v[70:71], v[28:29]
	v_pk_fma_f32 v[30:31], v[6:7], v[70:71], v[30:31]
	v_mov_b32_dpp v34, v35 row_ror:8 row_mask:0xf bank_mask:0xf
	v_add_f32_e32 v16, v28, v29
	v_add_f32_e32 v17, v30, v31
	v_cndmask_b32_e64 v32, v34, v35, s[6:7]
	v_cndmask_b32_e64 v33, v35, v34, s[6:7]
	v_cndmask_b32_e64 v18, v16, v17, s[6:7]
	v_cndmask_b32_e64 v19, v17, v16, s[6:7]
	v_pk_add_f32 v[8:9], v[32:33], v[38:39] neg_lo:[1,1] neg_hi:[1,1]
	s_nop 0
	v_add_f32_dpp v36, v18, v19 row_ror:8 row_mask:0xf bank_mask:0xf bound_ctrl:1
	ds_write_b32 v13, v36 offset:3840
	s_add_i32 s0, s0, 1
	s_waitcnt lgkmcnt(0)
	s_barrier
	s_cmpk_eq_i32 s0, 0x100
	s_cbranch_scc0 .Lsc_chunk
	s_setprio 0
	s_cmp_lg_u32 s14, 0
	s_cbranch_scc1 .LBB0_674
	v_readlane_b32 s0, v253, 16
	v_readlane_b32 s1, v253, 17
	s_nop 3
	s_add_u32 s0, s0, 0xec00000
	s_addc_u32 s1, s1, 0
	s_nop 3
	global_store_dwordx4 v49, v[0:3], s[0:1]
	global_store_dwordx4 v49, v[4:7], s[0:1] offset:256
